# phase 0 adaLN GEMV: 32 strided row loads in flight per batch (four value sets)
# baseline (speedup 1.0000x reference)
.LBB0_98:
	v_lshl_add_u64 v[36:37], v[2:3], 0, s[10:11]
	v_add_co_u32_e32 v38, vcc, s53, v36
	s_mov_b32 s9, 0xc000
	s_nop 0
	v_addc_co_u32_e32 v39, vcc, 0, v37, vcc
	v_add_co_u32_e32 v40, vcc, s9, v36
	s_mov_b32 s9, 0x12000
	s_nop 0
	v_addc_co_u32_e32 v41, vcc, 0, v37, vcc
	v_add_co_u32_e32 v42, vcc, s9, v36
	s_mov_b32 s9, 0x18000
	s_nop 0
	v_addc_co_u32_e32 v43, vcc, 0, v37, vcc
	global_load_dword v60, v[36:37], off
	v_add_co_u32_e32 v44, vcc, s9, v36
	s_mov_b32 s9, 0x1e000
	s_nop 0
	v_addc_co_u32_e32 v45, vcc, 0, v37, vcc
	v_add_co_u32_e32 v46, vcc, s9, v36
	s_mov_b32 s9, 0x24000
	s_nop 0
	v_addc_co_u32_e32 v47, vcc, 0, v37, vcc
	v_add_co_u32_e32 v48, vcc, s9, v36
	s_mov_b32 s9, 0x2a000
	s_nop 0
	v_addc_co_u32_e32 v49, vcc, 0, v37, vcc
	v_add_co_u32_e32 v36, vcc, s9, v36
	s_add_u32 s10, s10, 0x30000
	s_nop 0
	v_addc_co_u32_e32 v37, vcc, 0, v37, vcc
	global_load_dword v62, v[38:39], off
	global_load_dword v64, v[40:41], off
	global_load_dword v66, v[42:43], off
	global_load_dword v68, v[44:45], off
	global_load_dword v70, v[46:47], off
	global_load_dword v72, v[48:49], off
	global_load_dword v74, v[36:37], off
	v_lshl_add_u64 v[36:37], v[2:3], 0, s[10:11]
	v_add_co_u32_e32 v38, vcc, s53, v36
	s_mov_b32 s9, 0xc000
	s_nop 0
	v_addc_co_u32_e32 v39, vcc, 0, v37, vcc
	v_add_co_u32_e32 v40, vcc, s9, v36
	s_mov_b32 s9, 0x12000
	s_nop 0
	v_addc_co_u32_e32 v41, vcc, 0, v37, vcc
	v_add_co_u32_e32 v42, vcc, s9, v36
	s_mov_b32 s9, 0x18000
	s_nop 0
	v_addc_co_u32_e32 v43, vcc, 0, v37, vcc
	global_load_dword v78, v[36:37], off
	v_add_co_u32_e32 v44, vcc, s9, v36
	s_mov_b32 s9, 0x1e000
	s_nop 0
	v_addc_co_u32_e32 v45, vcc, 0, v37, vcc
	v_add_co_u32_e32 v46, vcc, s9, v36
	s_mov_b32 s9, 0x24000
	s_nop 0
	v_addc_co_u32_e32 v47, vcc, 0, v37, vcc
	v_add_co_u32_e32 v48, vcc, s9, v36
	s_mov_b32 s9, 0x2a000
	s_nop 0
	v_addc_co_u32_e32 v49, vcc, 0, v37, vcc
	v_add_co_u32_e32 v36, vcc, s9, v36
	s_add_u32 s10, s10, 0x30000
	s_nop 0
	v_addc_co_u32_e32 v37, vcc, 0, v37, vcc
	global_load_dword v80, v[38:39], off
	global_load_dword v82, v[40:41], off
	global_load_dword v84, v[42:43], off
	global_load_dword v86, v[44:45], off
	global_load_dword v88, v[46:47], off
	global_load_dword v90, v[48:49], off
	global_load_dword v92, v[36:37], off
	v_lshl_add_u64 v[36:37], v[2:3], 0, s[10:11]
	v_add_co_u32_e32 v38, vcc, s53, v36
	s_mov_b32 s9, 0xc000
	s_nop 0
	v_addc_co_u32_e32 v39, vcc, 0, v37, vcc
	v_add_co_u32_e32 v40, vcc, s9, v36
	s_mov_b32 s9, 0x12000
	s_nop 0
	v_addc_co_u32_e32 v41, vcc, 0, v37, vcc
	v_add_co_u32_e32 v42, vcc, s9, v36
	s_mov_b32 s9, 0x18000
	s_nop 0
	v_addc_co_u32_e32 v43, vcc, 0, v37, vcc
	global_load_dword v96, v[36:37], off
	v_add_co_u32_e32 v44, vcc, s9, v36
	s_mov_b32 s9, 0x1e000
	s_nop 0
	v_addc_co_u32_e32 v45, vcc, 0, v37, vcc
	v_add_co_u32_e32 v46, vcc, s9, v36
	s_mov_b32 s9, 0x24000
	s_nop 0
	v_addc_co_u32_e32 v47, vcc, 0, v37, vcc
	v_add_co_u32_e32 v48, vcc, s9, v36
	s_mov_b32 s9, 0x2a000
	s_nop 0
	v_addc_co_u32_e32 v49, vcc, 0, v37, vcc
	v_add_co_u32_e32 v36, vcc, s9, v36
	s_add_u32 s10, s10, 0x30000
	s_nop 0
	v_addc_co_u32_e32 v37, vcc, 0, v37, vcc
	global_load_dword v98, v[38:39], off
	global_load_dword v100, v[40:41], off
	global_load_dword v102, v[42:43], off
	global_load_dword v104, v[44:45], off
	global_load_dword v106, v[46:47], off
	global_load_dword v108, v[48:49], off
	global_load_dword v110, v[36:37], off
	v_lshl_add_u64 v[36:37], v[2:3], 0, s[10:11]
	v_add_co_u32_e32 v38, vcc, s53, v36
	s_mov_b32 s9, 0xc000
	s_nop 0
	v_addc_co_u32_e32 v39, vcc, 0, v37, vcc
	v_add_co_u32_e32 v40, vcc, s9, v36
	s_mov_b32 s9, 0x12000
	s_nop 0
	v_addc_co_u32_e32 v41, vcc, 0, v37, vcc
	v_add_co_u32_e32 v42, vcc, s9, v36
	s_mov_b32 s9, 0x18000
	s_nop 0
	v_addc_co_u32_e32 v43, vcc, 0, v37, vcc
	global_load_dword v114, v[36:37], off
	v_add_co_u32_e32 v44, vcc, s9, v36
	s_mov_b32 s9, 0x1e000
	s_nop 0
	v_addc_co_u32_e32 v45, vcc, 0, v37, vcc
	v_add_co_u32_e32 v46, vcc, s9, v36
	s_mov_b32 s9, 0x24000
	s_nop 0
	v_addc_co_u32_e32 v47, vcc, 0, v37, vcc
	v_add_co_u32_e32 v48, vcc, s9, v36
	s_mov_b32 s9, 0x2a000
	s_nop 0
	v_addc_co_u32_e32 v49, vcc, 0, v37, vcc
	v_add_co_u32_e32 v36, vcc, s9, v36
	s_add_u32 s10, s10, 0x30000
	s_nop 0
	v_addc_co_u32_e32 v37, vcc, 0, v37, vcc
	global_load_dword v116, v[38:39], off
	global_load_dword v118, v[40:41], off
	global_load_dword v120, v[42:43], off
	global_load_dword v122, v[44:45], off
	global_load_dword v124, v[46:47], off
	global_load_dword v126, v[48:49], off
	global_load_dword v128, v[36:37], off
	ds_read_b128 v[36:39], v34
	ds_read_b128 v[40:43], v34 offset:16
	ds_read_b128 v[44:47], v34 offset:4096
	ds_read_b128 v[48:51], v34 offset:4112
	ds_read_b128 v[52:55], v34 offset:8192
	ds_read_b128 v[56:59], v34 offset:8208
	s_waitcnt lgkmcnt(5)
	v_mov_b32_e32 v76, v36
	s_waitcnt lgkmcnt(3)
	v_mov_b32_e32 v77, v44
	v_mov_b32_e32 v44, v37
	v_mov_b32_e32 v36, v38
	v_mov_b32_e32 v37, v46
	v_mov_b32_e32 v46, v39
	v_mov_b32_e32 v38, v40
	s_waitcnt lgkmcnt(2)
	v_mov_b32_e32 v39, v48
	v_mov_b32_e32 v48, v41
	v_mov_b32_e32 v40, v42
	v_mov_b32_e32 v41, v50
	v_mov_b32_e32 v50, v43
	v_add_u32_e32 v34, 32, v34
	s_waitcnt vmcnt(31)
	v_pk_fma_f32 v[4:5], v[76:77], v[60:61], v[4:5] op_sel_hi:[1,0,1]
	s_waitcnt lgkmcnt(1)
	v_fmac_f32_e32 v18, v52, v60
	s_waitcnt vmcnt(30)
	v_pk_fma_f32 v[4:5], v[44:45], v[62:63], v[4:5] op_sel_hi:[1,0,1]
	v_fmac_f32_e32 v18, v53, v62
	s_waitcnt vmcnt(29)
	v_pk_fma_f32 v[4:5], v[36:37], v[64:65], v[4:5] op_sel_hi:[1,0,1]
	v_fmac_f32_e32 v18, v54, v64
	s_waitcnt vmcnt(28)
	v_pk_fma_f32 v[4:5], v[46:47], v[66:67], v[4:5] op_sel_hi:[1,0,1]
	v_fmac_f32_e32 v18, v55, v66
	s_waitcnt vmcnt(27)
	v_pk_fma_f32 v[4:5], v[38:39], v[68:69], v[4:5] op_sel_hi:[1,0,1]
	s_waitcnt lgkmcnt(0)
	v_fmac_f32_e32 v18, v56, v68
	s_waitcnt vmcnt(26)
	v_pk_fma_f32 v[4:5], v[48:49], v[70:71], v[4:5] op_sel_hi:[1,0,1]
	v_fmac_f32_e32 v18, v57, v70
	s_waitcnt vmcnt(25)
	v_pk_fma_f32 v[4:5], v[40:41], v[72:73], v[4:5] op_sel_hi:[1,0,1]
	v_fmac_f32_e32 v18, v58, v72
	s_waitcnt vmcnt(24)
	v_pk_fma_f32 v[4:5], v[50:51], v[74:75], v[4:5] op_sel_hi:[1,0,1]
	v_fmac_f32_e32 v18, v59, v74
	ds_read_b128 v[36:39], v34
	ds_read_b128 v[40:43], v34 offset:16
	ds_read_b128 v[44:47], v34 offset:4096
	ds_read_b128 v[48:51], v34 offset:4112
	ds_read_b128 v[52:55], v34 offset:8192
	ds_read_b128 v[56:59], v34 offset:8208
	s_waitcnt lgkmcnt(5)
	v_mov_b32_e32 v76, v36
	s_waitcnt lgkmcnt(3)
	v_mov_b32_e32 v77, v44
	v_mov_b32_e32 v44, v37
	v_mov_b32_e32 v36, v38
	v_mov_b32_e32 v37, v46
	v_mov_b32_e32 v46, v39
	v_mov_b32_e32 v38, v40
	s_waitcnt lgkmcnt(2)
	v_mov_b32_e32 v39, v48
	v_mov_b32_e32 v48, v41
	v_mov_b32_e32 v40, v42
	v_mov_b32_e32 v41, v50
	v_mov_b32_e32 v50, v43
	v_add_u32_e32 v34, 32, v34
	s_waitcnt vmcnt(23)
	v_pk_fma_f32 v[4:5], v[76:77], v[78:79], v[4:5] op_sel_hi:[1,0,1]
	s_waitcnt lgkmcnt(1)
	v_fmac_f32_e32 v18, v52, v78
	s_waitcnt vmcnt(22)
	v_pk_fma_f32 v[4:5], v[44:45], v[80:81], v[4:5] op_sel_hi:[1,0,1]
	v_fmac_f32_e32 v18, v53, v80
	s_waitcnt vmcnt(21)
	v_pk_fma_f32 v[4:5], v[36:37], v[82:83], v[4:5] op_sel_hi:[1,0,1]
	v_fmac_f32_e32 v18, v54, v82
	s_waitcnt vmcnt(20)
	v_pk_fma_f32 v[4:5], v[46:47], v[84:85], v[4:5] op_sel_hi:[1,0,1]
	v_fmac_f32_e32 v18, v55, v84
	s_waitcnt vmcnt(19)
	v_pk_fma_f32 v[4:5], v[38:39], v[86:87], v[4:5] op_sel_hi:[1,0,1]
	s_waitcnt lgkmcnt(0)
	v_fmac_f32_e32 v18, v56, v86
	s_waitcnt vmcnt(18)
	v_pk_fma_f32 v[4:5], v[48:49], v[88:89], v[4:5] op_sel_hi:[1,0,1]
	v_fmac_f32_e32 v18, v57, v88
	s_waitcnt vmcnt(17)
	v_pk_fma_f32 v[4:5], v[40:41], v[90:91], v[4:5] op_sel_hi:[1,0,1]
	v_fmac_f32_e32 v18, v58, v90
	s_waitcnt vmcnt(16)
	v_pk_fma_f32 v[4:5], v[50:51], v[92:93], v[4:5] op_sel_hi:[1,0,1]
	v_fmac_f32_e32 v18, v59, v92
	ds_read_b128 v[36:39], v34
	ds_read_b128 v[40:43], v34 offset:16
	ds_read_b128 v[44:47], v34 offset:4096
	ds_read_b128 v[48:51], v34 offset:4112
	ds_read_b128 v[52:55], v34 offset:8192
	ds_read_b128 v[56:59], v34 offset:8208
	s_waitcnt lgkmcnt(5)
	v_mov_b32_e32 v76, v36
	s_waitcnt lgkmcnt(3)
	v_mov_b32_e32 v77, v44
	v_mov_b32_e32 v44, v37
	v_mov_b32_e32 v36, v38
	v_mov_b32_e32 v37, v46
	v_mov_b32_e32 v46, v39
	v_mov_b32_e32 v38, v40
	s_waitcnt lgkmcnt(2)
	v_mov_b32_e32 v39, v48
	v_mov_b32_e32 v48, v41
	v_mov_b32_e32 v40, v42
	v_mov_b32_e32 v41, v50
	v_mov_b32_e32 v50, v43
	v_add_u32_e32 v34, 32, v34
	s_waitcnt vmcnt(15)
	v_pk_fma_f32 v[4:5], v[76:77], v[96:97], v[4:5] op_sel_hi:[1,0,1]
	s_waitcnt lgkmcnt(1)
	v_fmac_f32_e32 v18, v52, v96
	s_waitcnt vmcnt(14)
	v_pk_fma_f32 v[4:5], v[44:45], v[98:99], v[4:5] op_sel_hi:[1,0,1]
	v_fmac_f32_e32 v18, v53, v98
	s_waitcnt vmcnt(13)
	v_pk_fma_f32 v[4:5], v[36:37], v[100:101], v[4:5] op_sel_hi:[1,0,1]
	v_fmac_f32_e32 v18, v54, v100
	s_waitcnt vmcnt(12)
	v_pk_fma_f32 v[4:5], v[46:47], v[102:103], v[4:5] op_sel_hi:[1,0,1]
	v_fmac_f32_e32 v18, v55, v102
	s_waitcnt vmcnt(11)
	v_pk_fma_f32 v[4:5], v[38:39], v[104:105], v[4:5] op_sel_hi:[1,0,1]
	s_waitcnt lgkmcnt(0)
	v_fmac_f32_e32 v18, v56, v104
	s_waitcnt vmcnt(10)
	v_pk_fma_f32 v[4:5], v[48:49], v[106:107], v[4:5] op_sel_hi:[1,0,1]
	v_fmac_f32_e32 v18, v57, v106
	s_waitcnt vmcnt(9)
	v_pk_fma_f32 v[4:5], v[40:41], v[108:109], v[4:5] op_sel_hi:[1,0,1]
	v_fmac_f32_e32 v18, v58, v108
	s_waitcnt vmcnt(8)
	v_pk_fma_f32 v[4:5], v[50:51], v[110:111], v[4:5] op_sel_hi:[1,0,1]
	v_fmac_f32_e32 v18, v59, v110
	ds_read_b128 v[36:39], v34
	ds_read_b128 v[40:43], v34 offset:16
	ds_read_b128 v[44:47], v34 offset:4096
	ds_read_b128 v[48:51], v34 offset:4112
	ds_read_b128 v[52:55], v34 offset:8192
	ds_read_b128 v[56:59], v34 offset:8208
	s_waitcnt lgkmcnt(5)
	v_mov_b32_e32 v76, v36
	s_waitcnt lgkmcnt(3)
	v_mov_b32_e32 v77, v44
	v_mov_b32_e32 v44, v37
	v_mov_b32_e32 v36, v38
	v_mov_b32_e32 v37, v46
	v_mov_b32_e32 v46, v39
	v_mov_b32_e32 v38, v40
	s_waitcnt lgkmcnt(2)
	v_mov_b32_e32 v39, v48
	v_mov_b32_e32 v48, v41
	v_mov_b32_e32 v40, v42
	v_mov_b32_e32 v41, v50
	v_mov_b32_e32 v50, v43
	v_add_u32_e32 v34, 32, v34
	s_cmp_eq_u32 s10, 0x300000
	s_waitcnt vmcnt(7)
	v_pk_fma_f32 v[4:5], v[76:77], v[114:115], v[4:5] op_sel_hi:[1,0,1]
	s_waitcnt lgkmcnt(1)
	v_fmac_f32_e32 v18, v52, v114
	s_waitcnt vmcnt(6)
	v_pk_fma_f32 v[4:5], v[44:45], v[116:117], v[4:5] op_sel_hi:[1,0,1]
	v_fmac_f32_e32 v18, v53, v116
	s_waitcnt vmcnt(5)
	v_pk_fma_f32 v[4:5], v[36:37], v[118:119], v[4:5] op_sel_hi:[1,0,1]
	v_fmac_f32_e32 v18, v54, v118
	s_waitcnt vmcnt(4)
	v_pk_fma_f32 v[4:5], v[46:47], v[120:121], v[4:5] op_sel_hi:[1,0,1]
	v_fmac_f32_e32 v18, v55, v120
	s_waitcnt vmcnt(3)
	v_pk_fma_f32 v[4:5], v[38:39], v[122:123], v[4:5] op_sel_hi:[1,0,1]
	s_waitcnt lgkmcnt(0)
	v_fmac_f32_e32 v18, v56, v122
	s_waitcnt vmcnt(2)
	v_pk_fma_f32 v[4:5], v[48:49], v[124:125], v[4:5] op_sel_hi:[1,0,1]
	v_fmac_f32_e32 v18, v57, v124
	s_waitcnt vmcnt(1)
	v_pk_fma_f32 v[4:5], v[40:41], v[126:127], v[4:5] op_sel_hi:[1,0,1]
	v_fmac_f32_e32 v18, v58, v126
	s_waitcnt vmcnt(0)
	v_pk_fma_f32 v[4:5], v[50:51], v[128:129], v[4:5] op_sel_hi:[1,0,1]
	v_fmac_f32_e32 v18, v59, v128
	s_cbranch_scc0 .LBB0_98
	s_barrier
	ds_write2st64_b32 v21, v4, v5 offset0:48 offset1:49
	ds_write_b32 v21, v18 offset:12800
	s_waitcnt lgkmcnt(0)
	s_barrier
	s_and_saveexec_b64 s[10:11], s[4:5]
	s_cbranch_execz .LBB0_41
	v_or_b32_e32 v2, s8, v9
	s_mul_i32 s8, s12, 0x1800
	v_add_u32_e32 v4, s8, v2
	v_readlane_b32 s36, v252, 2
	v_ashrrev_i32_e32 v5, 31, v4
	v_readlane_b32 s46, v252, 12
	v_readlane_b32 s47, v252, 13
	v_mad_u64_u32 v[40:41], s[8:9], s12, 3, v[8:9]
	s_nop 0
	v_lshl_add_u64 v[4:5], v[4:5], 2, s[46:47]
	global_load_dword v18, v[4:5], off
	ds_read2st64_b32 v[4:5], v22 offset0:48 offset1:51
	ds_read2st64_b32 v[34:35], v22 offset0:54 offset1:57
	ds_read2st64_b32 v[36:37], v22 offset0:60 offset1:63
	ds_read2st64_b32 v[38:39], v22 offset0:66 offset1:69
	v_mov_b64_e32 v[42:43], s[18:19]
	s_waitcnt lgkmcnt(3)
	v_add_f32_e32 v4, 0, v4
	v_add_f32_e32 v4, v4, v5
	s_waitcnt lgkmcnt(2)
	v_add_f32_e32 v4, v4, v34
	v_add_f32_e32 v4, v4, v35
	s_waitcnt lgkmcnt(1)
	v_add_f32_e32 v4, v4, v36
	v_add_f32_e32 v4, v4, v37
	s_waitcnt lgkmcnt(0)
	v_add_f32_e32 v4, v4, v38
	v_ashrrev_i32_e32 v3, 31, v2
	v_mad_i64_i32 v[40:41], s[8:9], v40, s53, v[42:43]
	v_add_f32_e32 v4, v4, v39
	v_lshl_add_u64 v[2:3], v[2:3], 2, v[40:41]
	v_readlane_b32 s37, v252, 3
	v_readlane_b32 s38, v252, 4
	v_readlane_b32 s39, v252, 5
	v_readlane_b32 s40, v252, 6
	v_readlane_b32 s41, v252, 7
	v_readlane_b32 s42, v252, 8
	v_readlane_b32 s43, v252, 9
	v_readlane_b32 s44, v252, 10
	v_readlane_b32 s45, v252, 11
	v_readlane_b32 s48, v252, 14
	v_readlane_b32 s49, v252, 15
	v_readlane_b32 s50, v252, 16
	v_readlane_b32 s51, v252, 17
	s_waitcnt vmcnt(0)
	v_add_f32_e32 v4, v4, v18
	global_store_dword v[2:3], v4, off
	s_branch .LBB0_41

.LBB0_164:
.LBB0_165:
	s_cmp_ge_i32 s60, s61
	s_cbranch_scc1 .LBB0_532
	s_lshr_b32 s0, s3, 16
	s_and_b32 s1, s3, 0xffff
	s_and_b32 s4, 0xffff, s68
	s_add_u32 s7, s26, 0xa1d0000
	s_addc_u32 s2, s27, 0
	s_add_u32 s76, s26, 0x164d0000
	v_writelane_b32 v252, s2, 50
	s_addc_u32 s77, s27, 0
	s_lshl_b32 s2, s84, 3
	v_writelane_b32 v252, s2, 51
	s_add_u32 s2, s26, 0x60d0000
	s_addc_u32 s3, s27, 0
	s_lshl_b32 s74, s62, 3
	s_add_u32 s8, s26, 0xa1d0800
	s_addc_u32 s9, s27, 0
	s_add_u32 s10, s26, 0xa1d1000
	s_mul_i32 s6, s1, s4
	s_mul_i32 s5, s63, s62
	s_addc_u32 s63, s27, 0
	s_bfe_i32 s6, s6, 0x180000
	s_mul_i32 s0, s6, s0
	s_add_i32 s0, s0, 63
	v_bfe_u32 v2, v0, 10, 10
	v_bfe_u32 v3, v0, 20, 10
	v_and_b32_e32 v168, 0x3ff, v0
	s_andn2_b32 s0, s0, 63
	v_mad_u32_u24 v0, v3, s1, v2
	s_cmp_lg_u32 s0, 64
	v_mad_u64_u32 v[0:1], s[0:1], v0, s4, v[168:169]
	s_cselect_b64 s[90:91], -1, 0
	s_add_u32 s0, s26, 0x5ec8000
	s_addc_u32 s1, s27, 0
	s_add_u32 s92, s26, 0x5e80000
	s_addc_u32 s93, s27, 0
	s_add_u32 s94, s26, 0x5ed0000
	s_addc_u32 s95, s27, 0
	s_add_u32 s68, s26, 0x1e6d0200
	s_addc_u32 s69, s27, 0
	s_add_u32 s70, s26, 0x1e6d0400
	v_writelane_b32 v252, s2, 52
	s_addc_u32 s71, s27, 0
	s_add_u32 s80, s26, 0x1e6d0500
	v_writelane_b32 v252, s3, 53
	v_writelane_b32 v252, s0, 54
	s_addc_u32 s81, s27, 0
	s_mov_b32 s75, 0x11000
	v_writelane_b32 v252, s1, 55
	s_add_u32 s0, s26, 0x1e6d0600
	s_addc_u32 s1, s27, 0
	v_writelane_b32 v252, s0, 56
	v_or3_b32 v2, v168, v2, v3
	s_mul_i32 s65, s5, s33
	v_writelane_b32 v252, s1, 57
	s_add_u32 s0, s26, 0x1e6d0700
	s_addc_u32 s1, s27, 0
	v_writelane_b32 v252, s0, 58
	v_mbcnt_lo_u32_b32 v3, -1, 0
	v_lshrrev_b32_e32 v1, 6, v0
	v_writelane_b32 v252, s1, 59
	s_add_u32 s0, s26, 0x1e6d0800
	s_addc_u32 s1, s27, 0
	v_writelane_b32 v252, s0, 60
	v_mbcnt_hi_u32_b32 v197, -1, v3
	v_mov_b32_e32 v171, 0
	v_writelane_b32 v252, s1, 61
	s_add_u32 s0, s26, 0x1e6d0900
	s_addc_u32 s1, s27, 0
	v_writelane_b32 v252, s0, 62
	v_mov_b32_e32 v169, 0x358637bd
	v_mov_b32_e32 v173, 1
	v_writelane_b32 v252, s1, 63
	s_add_u32 s0, s26, 0x1e6d0a00
	s_addc_u32 s1, s27, 0
	v_writelane_b32 v251, s0, 0
	v_readlane_b32 s44, v252, 2
	v_mov_b32_e32 v192, 0x100
	v_writelane_b32 v251, s1, 1
	s_add_u32 s0, s26, 0x1e6d0b00
	s_addc_u32 s1, s27, 0
	v_writelane_b32 v251, s0, 2
	v_mov_b32_e32 v193, 0x3ef1014c
	v_mov_b32_e32 v194, 0x3e4ccccd
	v_writelane_b32 v251, s1, 3
	s_add_u32 s0, s26, 0x1e6d0c00
	s_addc_u32 s1, s27, 0
	v_writelane_b32 v251, s0, 4
	v_mov_b32_e32 v195, 0x1800
	v_bfrev_b32_e32 v196, 1
	v_writelane_b32 v251, s1, 5
	s_add_u32 s0, s26, 0x1e6d0d00
	s_addc_u32 s1, s27, 0
	v_writelane_b32 v251, s0, 6
	v_or_b32_e32 v198, v197, v1
	v_mov_b32_e32 v199, 0x3e38aa3b
	v_writelane_b32 v251, s1, 7
	s_add_u32 s0, s26, 0x1e6d0e00
	s_addc_u32 s1, s27, 0
	v_writelane_b32 v251, s0, 8
	v_mov_b32_e32 v172, 0xbf3a00e3
	s_movk_i32 s79, 0x60
	v_writelane_b32 v251, s1, 9
	s_add_u32 s0, s26, 0x1e6d0f00
	s_addc_u32 s1, s27, 0
	v_writelane_b32 v251, s0, 10
	s_mov_b32 s85, 0x800000
	s_mov_b32 s33, 0x30000
	v_writelane_b32 v251, s1, 11
	s_add_u32 s0, s26, 0x1e6d1000
	s_addc_u32 s1, s27, 0
	v_writelane_b32 v251, s0, 12
	s_mov_b32 s99, 0x47800000
	s_mov_b32 s89, 0x4138aa3b
	v_writelane_b32 v251, s1, 13
	s_add_u32 s0, s26, 0x1e6d1100
	s_addc_u32 s1, s27, 0
	v_writelane_b32 v251, s0, 14
	s_mov_b64 s[96:97], 0x180
	s_mov_b32 s98, 0x3e6d3388
	v_writelane_b32 v251, s1, 15
	s_add_u32 s0, s26, 0x1e6d1200
	s_addc_u32 s1, s27, 0
	v_writelane_b32 v251, s0, 16
	s_mov_b32 s72, 0x3f07dc22
	s_mov_b32 s4, 0
	v_writelane_b32 v251, s1, 17
	s_add_u32 s0, s26, 0x1e6d1300
	s_addc_u32 s1, s27, 0
	v_writelane_b32 v251, s0, 18
	s_cmp_eq_u32 s64, 15
	v_readlane_b32 s45, v252, 3
	v_writelane_b32 v251, s1, 19
	s_cselect_b64 s[0:1], -1, 0
	v_writelane_b32 v251, s0, 20
	s_cmp_eq_u32 s64, 14
	v_readlane_b32 s48, v252, 6
	v_writelane_b32 v251, s1, 21
	s_cselect_b64 s[0:1], -1, 0
	v_writelane_b32 v251, s0, 22
	s_cmp_eq_u32 s64, 13
	v_readlane_b32 s49, v252, 7
	v_writelane_b32 v251, s1, 23
	s_cselect_b64 s[0:1], -1, 0
	v_writelane_b32 v251, s0, 24
	s_cmp_eq_u32 s64, 12
	v_readlane_b32 s56, v252, 14
	v_writelane_b32 v251, s1, 25
	s_cselect_b64 s[0:1], -1, 0
	v_writelane_b32 v251, s0, 26
	s_cmp_eq_u32 s64, 11
	v_readlane_b32 s57, v252, 15
	v_writelane_b32 v251, s1, 27
	s_cselect_b64 s[0:1], -1, 0
	v_writelane_b32 v251, s0, 28
	s_cmp_eq_u32 s64, 10
	v_readlane_b32 s58, v252, 16
	v_writelane_b32 v251, s1, 29
	s_cselect_b64 s[0:1], -1, 0
	v_writelane_b32 v251, s0, 30
	s_cmp_eq_u32 s64, 9
	v_readlane_b32 s59, v252, 17
	v_writelane_b32 v251, s1, 31
	s_cselect_b64 s[0:1], -1, 0
	v_writelane_b32 v251, s0, 32
	s_cmp_eq_u32 s64, 8
	s_mov_b32 s78, s7
	v_writelane_b32 v251, s1, 33
	s_cselect_b64 s[0:1], -1, 0
	v_writelane_b32 v251, s0, 34
	s_cmp_eq_u32 s64, 7
	s_mov_b32 s73, s10
	v_writelane_b32 v251, s1, 35
	s_cselect_b64 s[0:1], -1, 0
	v_writelane_b32 v251, s0, 36
	s_cmp_eq_u32 s64, 6
	v_readlane_b32 s46, v252, 4
	v_writelane_b32 v251, s1, 37
	s_cselect_b64 s[0:1], -1, 0
	v_writelane_b32 v251, s0, 38
	s_cmp_eq_u32 s64, 5
	v_readlane_b32 s47, v252, 5
	v_writelane_b32 v251, s1, 39
	s_cselect_b64 s[0:1], -1, 0
	v_writelane_b32 v251, s0, 40
	s_cmp_eq_u32 s64, 4
	v_readlane_b32 s50, v252, 8
	v_writelane_b32 v251, s1, 41
	s_cselect_b64 s[0:1], -1, 0
	v_writelane_b32 v251, s0, 42
	s_cmp_eq_u32 s64, 3
	v_readlane_b32 s51, v252, 9
	v_writelane_b32 v251, s1, 43
	s_cselect_b64 s[0:1], -1, 0
	v_writelane_b32 v251, s0, 44
	s_cmp_eq_u32 s64, 2
	v_readlane_b32 s52, v252, 10
	v_writelane_b32 v251, s1, 45
	s_cselect_b64 s[0:1], -1, 0
	v_writelane_b32 v251, s0, 46
	s_cmp_eq_u32 s64, 1
	v_readlane_b32 s53, v252, 11
	v_writelane_b32 v251, s1, 47
	s_cselect_b64 s[0:1], -1, 0
	v_writelane_b32 v251, s0, 48
	s_cmp_eq_u32 s64, 0
	v_readlane_b32 s54, v252, 12
	v_writelane_b32 v251, s1, 49
	s_cselect_b64 s[0:1], -1, 0
	v_writelane_b32 v251, s0, 50
	v_readlane_b32 s55, v252, 13
	s_nop 0
	v_writelane_b32 v251, s1, 51
	s_lshl_b32 s0, s64, 8
	s_add_u32 s0, s66, s0
	s_addc_u32 s1, s67, 0
	s_add_u32 s2, s0, 0x1400
	s_addc_u32 s3, s1, 0
	v_writelane_b32 v251, s2, 52
	s_add_u32 s0, s0, 0x2400
	s_addc_u32 s1, s1, 0
	v_writelane_b32 v251, s3, 53
	v_writelane_b32 v251, s0, 54
	s_movk_i32 s64, 0x1000
	s_mov_b64 s[66:67], 0x100
	v_writelane_b32 v251, s1, 55
	s_add_u32 s0, s26, 0x1e6d3400
	s_addc_u32 s1, s27, 0
	v_writelane_b32 v251, s0, 56
	s_nop 1
	v_writelane_b32 v251, s1, 57
	s_add_u32 s0, s26, 0x1e6d3500
	s_addc_u32 s1, s27, 0
	v_writelane_b32 v251, s0, 58
	s_nop 1
	v_writelane_b32 v251, s1, 59
	s_lshl_b32 s0, s84, 7
	s_lshl_b32 s1, s62, 7
	v_writelane_b32 v251, s1, 60
	s_or_b32 s1, s0, 3
	v_writelane_b32 v251, s1, 61
	s_or_b32 s1, s0, 2
	v_writelane_b32 v251, s1, 62
	v_writelane_b32 v251, s0, 63
	s_or_b32 s0, s0, 1
	v_writelane_b32 v250, s0, 0
	s_add_u32 s0, s26, 0x180
	v_writelane_b32 v250, s0, 1
	s_addc_u32 s0, s27, 0
	v_writelane_b32 v250, s0, 2
	s_mov_b32 s0, 0x11200
	s_addk_i32 s0, 0x100
	v_writelane_b32 v250, s0, 3
	s_mov_b32 s0, 0x20000
	s_addk_i32 s0, 0x100
	v_writelane_b32 v250, s0, 4
	s_mov_b32 s0, 0x20004
	s_addk_i32 s0, 0x100
	v_writelane_b32 v250, s0, 5
	s_lshl_b32 s0, s84, 5
	v_writelane_b32 v250, s0, 6
	s_lshl_b32 s0, s62, 5
	v_writelane_b32 v250, s0, 7
	s_add_i32 s0, s75, 0x100
	v_writelane_b32 v250, s0, 8
	v_cmp_lt_u32_e64 s[0:1], 63, v0
	s_nop 1
	v_writelane_b32 v250, s0, 9
	s_nop 1
	v_writelane_b32 v250, s1, 10
	v_cmp_eq_u32_e64 s[0:1], 0, v2
	s_nop 1
	v_writelane_b32 v250, s0, 11
	s_nop 1
	v_writelane_b32 v250, s1, 12
	v_cmp_eq_u32_e64 s[0:1], 0, v168
	s_nop 1
	v_writelane_b32 v250, s0, 13
	s_nop 1
	v_writelane_b32 v250, s1, 14
	v_writelane_b32 v250, s7, 15
	v_writelane_b32 v250, s76, 16
	s_nop 1
	v_writelane_b32 v250, s77, 17
	v_writelane_b32 v250, s74, 18
	v_writelane_b32 v250, s8, 19
	s_nop 1
	v_writelane_b32 v250, s9, 20
	v_writelane_b32 v250, s10, 21
	v_writelane_b32 v250, s65, 22
	v_writelane_b32 v250, s68, 23
	s_nop 1
	v_writelane_b32 v250, s69, 24
	v_writelane_b32 v250, s70, 25
	s_nop 1
	v_writelane_b32 v250, s71, 26
	v_writelane_b32 v250, s80, 27
	s_nop 1
	v_writelane_b32 v250, s81, 28
	v_writelane_b32 v250, s86, 29
	s_nop 1
	v_writelane_b32 v250, s87, 30
	v_writelane_b32 v250, s63, 31
	v_writelane_b32 v250, s90, 32
	s_nop 1
	v_writelane_b32 v250, s91, 33
	v_writelane_b32 v250, s92, 34
	s_nop 1
	v_writelane_b32 v250, s93, 35
	v_writelane_b32 v250, s94, 36
	v_writelane_b32 v250, s95, 37
	v_writelane_b32 v250, s84, 38
	s_branch .LBB0_171
	s_nop 0
	s_nop 0
	s_nop 0
	s_nop 0
	s_nop 0
	s_nop 0
	s_nop 0
	s_nop 0
	s_nop 0
	s_nop 0
	s_nop 0
	s_nop 0
	s_nop 0
	s_nop 0
	s_nop 0
.LBB0_167:
	s_or_b64 exec, exec, s[8:9]
	s_waitcnt vmcnt(0)
	buffer_inv sc1
	s_waitcnt vmcnt(0)
